# best_b + unit-header tile-order division by the constant group size 4 as shift and mask (removes VALU rcp, v_readfirstlane and 20 SALU per tile)
# baseline (speedup 1.0000x reference)
.LBB0_244:
	s_add_i32 s83, s36, 1
	s_mul_i32 s4, s83, s74
	s_mul_hi_u32 s5, s83, s75
	s_add_i32 s5, s5, s4
	s_mul_i32 s4, s83, s75
	s_add_u32 s26, s4, s2
	s_addc_u32 s27, s5, s3
	v_cmp_gt_i64_e32 vcc, s[26:27], v[144:145]
	v_cmp_lt_i64_e64 s[4:5], s[26:27], v[142:143]
	s_cbranch_vccnz .LBB0_246
	s_ashr_i32 s16, s26, 31
	s_lshr_b32 s16, s16, 29
	s_add_i32 s16, s26, s16
	s_ashr_i32 s17, s16, 3
	s_and_b32 s16, s16, -8
	s_sub_i32 s16, s26, s16
	s_cmp_lt_i32 s16, 0
	s_cselect_b32 s18, s49, 0x2c0
	s_mul_i32 s16, s16, s18
	s_add_i32 s16, s16, s17
	s_mul_hi_i32 s17, s16, 0x2e8ba2e9
	s_lshr_b32 s18, s17, 31
	s_ashr_i32 s17, s17, 4
	s_add_i32 s17, s17, s18
	s_lshl_b32 s18, s17, 2
	s_sub_i32 s19, 0x100, s18
	s_min_i32 s19, s19, 4
	s_mulk_i32 s17, 0x58
	s_sub_i32 s17, s16, s17
	s_ashr_i32 s16, s17, 2
	s_and_b32 s17, s17, 3
	s_add_i32 s18, s18, s17

.LBB0_318:
	s_ashr_i32 s4, s18, 3
	s_add_i32 s4, s30, s4
	s_ashr_i32 s5, s4, 31
	s_lshr_b32 s5, s5, 28
	s_add_i32 s5, s4, s5
	s_ashr_i32 s18, s5, 4
	s_lshl_b32 s18, s18, 2
	s_sub_i32 s19, 0x100, s18
	s_min_i32 s19, s19, 4
	s_and_b32 s5, s5, -16
	s_sub_i32 s4, s4, s5
	s_ashr_i32 s74, s4, 2
	s_and_b32 s4, s4, 3
	s_add_i32 s75, s18, s4

.LBB0_488:
	s_add_i32 s80, s80, 1
	s_mul_i32 s1, s80, s61
	s_mul_hi_u32 s4, s80, s70
	s_add_i32 s4, s4, s1
	s_mul_i32 s1, s80, s70
	s_add_u32 s22, s1, s2
	s_addc_u32 s23, s4, s3
	v_cmp_gt_i64_e32 vcc, s[22:23], v[156:157]
	v_cmp_lt_i64_e64 s[4:5], s[22:23], v[154:155]
	s_cbranch_vccnz .LBB0_490
	s_ashr_i32 s1, s22, 31
	s_lshr_b32 s1, s1, 29
	s_add_i32 s1, s22, s1
	s_ashr_i32 s7, s1, 3
	s_and_b32 s1, s1, -8
	s_sub_i32 s1, s22, s1
	s_cmp_lt_i32 s1, 0
	s_cselect_b32 s8, s71, 0x1c0
	s_mul_i32 s1, s1, s8
	s_add_i32 s1, s1, s7
	s_mul_hi_i32 s7, s1, 0x92492493
	s_add_i32 s7, s7, s1
	s_lshr_b32 s8, s7, 31
	s_ashr_i32 s7, s7, 5
	s_add_i32 s7, s7, s8
	s_lshl_b32 s8, s7, 2
	s_sub_i32 s17, 0x100, s8
	s_min_i32 s17, s17, 4
	s_mul_i32 s7, s7, 56
	s_sub_i32 s1, s1, s7
	s_ashr_i32 s18, s1, 2
	s_and_b32 s1, s1, 3
	s_add_i32 s20, s8, s1

.LBB0_945:
	s_ashr_i32 s22, s24, 3
	s_add_i32 s22, s26, s22
	s_ashr_i32 s23, s22, 31
	s_lshr_b32 s23, s23, 28
	s_add_i32 s23, s22, s23
	s_ashr_i32 s24, s23, 4
	s_lshl_b32 s24, s24, 2
	s_sub_i32 s25, 0x100, s24
	s_min_i32 s25, s25, 4
	s_and_b32 s23, s23, -16
	s_sub_i32 s23, s22, s23
	s_ashr_i32 s22, s23, 2
	s_and_b32 s23, s23, 3
	s_add_i32 s24, s24, s23

.LBB0_1044:
	s_add_i32 s68, s28, 1
	s_mul_i32 s4, s68, s53
	s_mul_hi_u32 s5, s68, s54
	s_add_i32 s5, s5, s4
	s_mul_i32 s4, s68, s54
	s_add_u32 s20, s4, s2
	s_addc_u32 s21, s5, s3
	v_cmp_gt_i64_e32 vcc, s[20:21], v[144:145]
	v_cmp_lt_i64_e64 s[4:5], s[20:21], v[142:143]
	s_cbranch_vccnz .LBB0_1046
	s_ashr_i32 s16, s20, 31
	s_lshr_b32 s16, s16, 29
	s_add_i32 s16, s20, s16
	s_ashr_i32 s17, s16, 3
	s_and_b32 s16, s16, -8
	s_sub_i32 s16, s20, s16
	s_cmp_lt_i32 s16, 0
	s_cselect_b32 s18, s45, 0x2c0
	s_mul_i32 s16, s16, s18
	s_add_i32 s16, s16, s17
	s_mul_hi_i32 s17, s16, 0x2e8ba2e9
	s_lshr_b32 s18, s17, 31
	s_ashr_i32 s17, s17, 4
	s_add_i32 s17, s17, s18
	s_lshl_b32 s18, s17, 2
	s_sub_i32 s19, 0x100, s18
	s_min_i32 s19, s19, 4
	s_mulk_i32 s17, 0x58
	s_sub_i32 s17, s16, s17
	s_ashr_i32 s16, s17, 2
	s_and_b32 s17, s17, 3
	s_add_i32 s18, s18, s17

.LBB0_1118:
	s_ashr_i32 s0, s16, 3
	s_add_i32 s0, s22, s0
	s_ashr_i32 s1, s0, 31
	s_lshr_b32 s1, s1, 28
	s_add_i32 s1, s0, s1
	s_ashr_i32 s16, s1, 4
	s_lshl_b32 s16, s16, 2
	s_sub_i32 s17, 0x100, s16
	s_min_i32 s17, s17, 4
	s_and_b32 s1, s1, -16
	s_sub_i32 s0, s0, s1
	s_ashr_i32 s46, s0, 2
	s_and_b32 s0, s0, 3
	s_add_i32 s47, s16, s0
